# saddr-form LDS-DMA also in the P8, P6 and P10 K-loops (P6/P10: scalar base = panel + K offset formed by SALU)
# baseline (speedup 1.0000x reference)
.LBB0_658:
	s_add_u32 s30, s12, s42
	s_addc_u32 s31, s13, s43
	s_add_u32 s30, s30, 0x100
	s_addc_u32 s31, s31, 0
	s_add_u32 s44, s65, s42
	s_addc_u32 s45, s68, s43
	s_add_i32 s74, 0, 0x10000
	s_cmpk_eq_i32 s42, 0xf00
	s_cselect_b32 s47, s17, s31
	s_cselect_b32 s46, s69, s30
	s_cselect_b32 s45, s15, s45
	s_cselect_b32 s44, s72, s44
	s_add_i32 s75, 0, 0x14000
	v_add_u32_e32 v160, s74, v135
	v_add_u32_e32 v174, s75, v135
	ds_read_b128 v[148:151], v160
	ds_read_b128 v[152:155], v160 offset:1024
	ds_read_b128 v[156:159], v160 offset:2048
	ds_read_b128 v[160:163], v160 offset:3072
	ds_read_b128 v[164:167], v174
	ds_read_b128 v[170:173], v174 offset:1024
	ds_read_b128 v[178:181], v174 offset:2048
	ds_read_b128 v[182:185], v174 offset:3072
	s_add_u32 s84, s12, s42
	s_addc_u32 s85, s13, s43
	s_add_u32 s84, s84, 0x80080
	s_addc_u32 s85, s85, 0
	s_add_i32 m0, s52, 0xc000
	ds_read_b128 v[186:189], v147
	ds_read_b128 v[190:193], v147 offset:1024
	ds_read_b128 v[194:197], v147 offset:2048
	ds_read_b128 v[198:201], v147 offset:3072
	ds_read_b128 v[202:205], v147 offset:4096
	ds_read_b128 v[206:209], v147 offset:5120
	ds_read_b128 v[210:213], v147 offset:6144
	ds_read_b128 v[214:217], v147 offset:7168
	global_load_lds_dwordx4 v140, s[84:85]
	s_add_i32 m0, s52, 0xe000
	s_nop 0
	global_load_lds_dwordx4 v138, s[84:85]
	s_waitcnt vmcnt(8)
	s_waitcnt lgkmcnt(0)
	s_barrier
	s_setprio 1
	s_waitcnt lgkmcnt(0)
	v_mfma_f32_16x16x32_bf16 v[14:17], v[148:151], v[186:189], v[14:17]
	v_mfma_f32_16x16x32_bf16 v[10:13], v[156:159], v[186:189], v[10:13]
	v_mfma_f32_16x16x32_bf16 v[6:9], v[148:151], v[194:197], v[6:9]
	v_mfma_f32_16x16x32_bf16 v[2:5], v[156:159], v[194:197], v[2:5]
	v_mfma_f32_16x16x32_bf16 v[46:49], v[148:151], v[202:205], v[46:49]
	v_mfma_f32_16x16x32_bf16 v[42:45], v[156:159], v[202:205], v[42:45]
	v_mfma_f32_16x16x32_bf16 v[78:81], v[148:151], v[210:213], v[78:81]
	v_mfma_f32_16x16x32_bf16 v[74:77], v[156:159], v[210:213], v[74:77]
	v_mfma_f32_16x16x32_bf16 v[14:17], v[152:155], v[190:193], v[14:17]
	v_mfma_f32_16x16x32_bf16 v[10:13], v[160:163], v[190:193], v[10:13]
	v_mfma_f32_16x16x32_bf16 v[6:9], v[152:155], v[198:201], v[6:9]
	v_mfma_f32_16x16x32_bf16 v[2:5], v[160:163], v[198:201], v[2:5]
	v_mfma_f32_16x16x32_bf16 v[46:49], v[152:155], v[206:209], v[46:49]
	v_mfma_f32_16x16x32_bf16 v[42:45], v[160:163], v[206:209], v[42:45]
	v_mfma_f32_16x16x32_bf16 v[78:81], v[152:155], v[214:217], v[78:81]
	v_mfma_f32_16x16x32_bf16 v[74:77], v[160:163], v[214:217], v[74:77]
	s_setprio 0
	s_setprio 1
	v_mfma_f32_16x16x32_bf16 v[30:33], v[164:167], v[186:189], v[30:33]
	v_mfma_f32_16x16x32_bf16 v[26:29], v[178:181], v[186:189], v[26:29]
	v_mfma_f32_16x16x32_bf16 v[22:25], v[164:167], v[194:197], v[22:25]
	v_mfma_f32_16x16x32_bf16 v[18:21], v[178:181], v[194:197], v[18:21]
	v_mfma_f32_16x16x32_bf16 v[62:65], v[164:167], v[202:205], v[62:65]
	v_mfma_f32_16x16x32_bf16 v[58:61], v[178:181], v[202:205], v[58:61]
	v_mfma_f32_16x16x32_bf16 v[86:89], v[164:167], v[210:213], v[86:89]
	v_mfma_f32_16x16x32_bf16 v[82:85], v[178:181], v[210:213], v[82:85]
	v_mfma_f32_16x16x32_bf16 v[30:33], v[170:173], v[190:193], v[30:33]
	v_mfma_f32_16x16x32_bf16 v[26:29], v[182:185], v[190:193], v[26:29]
	v_mfma_f32_16x16x32_bf16 v[22:25], v[170:173], v[198:201], v[22:25]
	v_mfma_f32_16x16x32_bf16 v[18:21], v[182:185], v[198:201], v[18:21]
	v_mfma_f32_16x16x32_bf16 v[62:65], v[170:173], v[206:209], v[62:65]
	v_mfma_f32_16x16x32_bf16 v[58:61], v[182:185], v[206:209], v[58:61]
	v_mfma_f32_16x16x32_bf16 v[86:89], v[170:173], v[214:217], v[86:89]
	v_mfma_f32_16x16x32_bf16 v[82:85], v[182:185], v[214:217], v[82:85]
	s_setprio 0
	s_barrier
	s_add_i32 s30, s74, s29
	s_mov_b32 m0, s30
	ds_read_b128 v[186:189], v147 offset:16384
	ds_read_b128 v[190:193], v147 offset:17408
	ds_read_b128 v[194:197], v147 offset:18432
	ds_read_b128 v[198:201], v147 offset:19456
	ds_read_b128 v[202:205], v147 offset:20480
	ds_read_b128 v[206:209], v147 offset:21504
	ds_read_b128 v[210:213], v147 offset:22528
	ds_read_b128 v[214:217], v147 offset:23552
	global_load_lds_dwordx4 v0, s[44:45]
	s_add_i32 m0, s30, 0x2000
	s_add_u32 s30, s44, 0x80000
	s_mov_b64 s[78:79], s[44:45]
	s_addc_u32 s31, s45, 0
	s_add_i32 s74, s75, s29
	global_load_lds_dwordx4 v130, s[44:45]
	s_mov_b32 m0, s74
	s_nop 0
	global_load_lds_dwordx4 v0, s[30:31]
	s_add_i32 m0, s74, 0x2000
	s_nop 0
	global_load_lds_dwordx4 v130, s[30:31]
	s_mov_b32 m0, s52
	s_nop 0
	global_load_lds_dwordx4 v136, s[46:47]
	s_mov_b32 m0, s54
	s_nop 0
	global_load_lds_dwordx4 v132, s[46:47]
	s_waitcnt vmcnt(8)
	s_waitcnt lgkmcnt(0)
	s_barrier
	s_setprio 1
	s_waitcnt lgkmcnt(0)
	v_mfma_f32_16x16x32_bf16 v[102:105], v[148:151], v[186:189], v[102:105]
	v_mfma_f32_16x16x32_bf16 v[98:101], v[156:159], v[186:189], v[98:101]
	v_mfma_f32_16x16x32_bf16 v[126:129], v[148:151], v[194:197], v[126:129]
	v_mfma_f32_16x16x32_bf16 v[122:125], v[156:159], v[194:197], v[122:125]
	v_mfma_f32_16x16x32_bf16 v[94:97], v[148:151], v[202:205], v[94:97]
	v_mfma_f32_16x16x32_bf16 v[90:93], v[156:159], v[202:205], v[90:93]
	v_mfma_f32_16x16x32_bf16 v[54:57], v[148:151], v[210:213], v[54:57]
	v_mfma_f32_16x16x32_bf16 v[50:53], v[156:159], v[210:213], v[50:53]
	v_mfma_f32_16x16x32_bf16 v[102:105], v[152:155], v[190:193], v[102:105]
	v_mfma_f32_16x16x32_bf16 v[98:101], v[160:163], v[190:193], v[98:101]
	v_mfma_f32_16x16x32_bf16 v[126:129], v[152:155], v[198:201], v[126:129]
	v_mfma_f32_16x16x32_bf16 v[122:125], v[160:163], v[198:201], v[122:125]
	v_mfma_f32_16x16x32_bf16 v[94:97], v[152:155], v[206:209], v[94:97]
	v_mfma_f32_16x16x32_bf16 v[90:93], v[160:163], v[206:209], v[90:93]
	v_mfma_f32_16x16x32_bf16 v[54:57], v[152:155], v[214:217], v[54:57]
	v_mfma_f32_16x16x32_bf16 v[50:53], v[160:163], v[214:217], v[50:53]
	s_setprio 0
	s_setprio 1
	v_mfma_f32_16x16x32_bf16 v[118:121], v[164:167], v[186:189], v[118:121]
	v_mfma_f32_16x16x32_bf16 v[114:117], v[178:181], v[186:189], v[114:117]
	v_mfma_f32_16x16x32_bf16 v[110:113], v[164:167], v[194:197], v[110:113]
	v_mfma_f32_16x16x32_bf16 v[106:109], v[178:181], v[194:197], v[106:109]
	v_mfma_f32_16x16x32_bf16 v[70:73], v[164:167], v[202:205], v[70:73]
	v_mfma_f32_16x16x32_bf16 v[66:69], v[178:181], v[202:205], v[66:69]
	v_mfma_f32_16x16x32_bf16 v[38:41], v[164:167], v[210:213], v[38:41]
	v_mfma_f32_16x16x32_bf16 v[34:37], v[178:181], v[210:213], v[34:37]
	v_mfma_f32_16x16x32_bf16 v[118:121], v[170:173], v[190:193], v[118:121]
	v_mfma_f32_16x16x32_bf16 v[114:117], v[182:185], v[190:193], v[114:117]
	v_mfma_f32_16x16x32_bf16 v[110:113], v[170:173], v[198:201], v[110:113]
	v_mfma_f32_16x16x32_bf16 v[106:109], v[182:185], v[198:201], v[106:109]
	v_mfma_f32_16x16x32_bf16 v[70:73], v[170:173], v[206:209], v[70:73]
	v_mfma_f32_16x16x32_bf16 v[66:69], v[182:185], v[206:209], v[66:69]
	v_mfma_f32_16x16x32_bf16 v[38:41], v[170:173], v[214:217], v[38:41]
	v_mfma_f32_16x16x32_bf16 v[34:37], v[182:185], v[214:217], v[34:37]
	s_setprio 0
	s_barrier
	s_add_i32 s74, 0, 0x18000
	s_add_i32 s75, 0, 0x1c000
	v_add_u32_e32 v160, s74, v135
	v_add_u32_e32 v177, s75, v135
	ds_read_b128 v[148:151], v160
	ds_read_b128 v[152:155], v160 offset:1024
	ds_read_b128 v[156:159], v160 offset:2048
	ds_read_b128 v[160:163], v160 offset:3072
	ds_read_b128 v[164:167], v177
	ds_read_b128 v[170:173], v177 offset:1024
	ds_read_b128 v[178:181], v177 offset:2048
	ds_read_b128 v[182:185], v177 offset:3072
	s_add_u32 s30, s46, 0x80000
	s_addc_u32 s31, s47, 0
	s_mov_b32 m0, s55
	ds_read_b128 v[186:189], v147 offset:32768
	ds_read_b128 v[190:193], v147 offset:33792
	ds_read_b128 v[194:197], v147 offset:34816
	ds_read_b128 v[198:201], v147 offset:35840
	ds_read_b128 v[202:205], v147 offset:36864
	ds_read_b128 v[206:209], v147 offset:37888
	ds_read_b128 v[210:213], v147 offset:38912
	ds_read_b128 v[214:217], v147 offset:39936
	global_load_lds_dwordx4 v136, s[30:31]
	s_mov_b32 m0, s60
	s_nop 0
	global_load_lds_dwordx4 v132, s[30:31]
	s_waitcnt vmcnt(8)
	s_waitcnt lgkmcnt(0)
	s_barrier
	s_setprio 1
	s_waitcnt lgkmcnt(0)
	v_mfma_f32_16x16x32_bf16 v[14:17], v[148:151], v[186:189], v[14:17]
	v_mfma_f32_16x16x32_bf16 v[10:13], v[156:159], v[186:189], v[10:13]
	v_mfma_f32_16x16x32_bf16 v[6:9], v[148:151], v[194:197], v[6:9]
	v_mfma_f32_16x16x32_bf16 v[2:5], v[156:159], v[194:197], v[2:5]
	v_mfma_f32_16x16x32_bf16 v[46:49], v[148:151], v[202:205], v[46:49]
	v_mfma_f32_16x16x32_bf16 v[42:45], v[156:159], v[202:205], v[42:45]
	v_mfma_f32_16x16x32_bf16 v[78:81], v[148:151], v[210:213], v[78:81]
	v_mfma_f32_16x16x32_bf16 v[74:77], v[156:159], v[210:213], v[74:77]
	v_mfma_f32_16x16x32_bf16 v[14:17], v[152:155], v[190:193], v[14:17]
	v_mfma_f32_16x16x32_bf16 v[10:13], v[160:163], v[190:193], v[10:13]
	v_mfma_f32_16x16x32_bf16 v[6:9], v[152:155], v[198:201], v[6:9]
	v_mfma_f32_16x16x32_bf16 v[2:5], v[160:163], v[198:201], v[2:5]
	v_mfma_f32_16x16x32_bf16 v[46:49], v[152:155], v[206:209], v[46:49]
	v_mfma_f32_16x16x32_bf16 v[42:45], v[160:163], v[206:209], v[42:45]
	v_mfma_f32_16x16x32_bf16 v[78:81], v[152:155], v[214:217], v[78:81]
	v_mfma_f32_16x16x32_bf16 v[74:77], v[160:163], v[214:217], v[74:77]
	s_setprio 0
	s_setprio 1
	v_mfma_f32_16x16x32_bf16 v[30:33], v[164:167], v[186:189], v[30:33]
	v_mfma_f32_16x16x32_bf16 v[26:29], v[178:181], v[186:189], v[26:29]
	v_mfma_f32_16x16x32_bf16 v[22:25], v[164:167], v[194:197], v[22:25]
	v_mfma_f32_16x16x32_bf16 v[18:21], v[178:181], v[194:197], v[18:21]
	v_mfma_f32_16x16x32_bf16 v[62:65], v[164:167], v[202:205], v[62:65]
	v_mfma_f32_16x16x32_bf16 v[58:61], v[178:181], v[202:205], v[58:61]
	v_mfma_f32_16x16x32_bf16 v[86:89], v[164:167], v[210:213], v[86:89]
	v_mfma_f32_16x16x32_bf16 v[82:85], v[178:181], v[210:213], v[82:85]
	v_mfma_f32_16x16x32_bf16 v[30:33], v[170:173], v[190:193], v[30:33]
	v_mfma_f32_16x16x32_bf16 v[26:29], v[182:185], v[190:193], v[26:29]
	v_mfma_f32_16x16x32_bf16 v[22:25], v[170:173], v[198:201], v[22:25]
	v_mfma_f32_16x16x32_bf16 v[18:21], v[182:185], v[198:201], v[18:21]
	v_mfma_f32_16x16x32_bf16 v[62:65], v[170:173], v[206:209], v[62:65]
	v_mfma_f32_16x16x32_bf16 v[58:61], v[182:185], v[206:209], v[58:61]
	v_mfma_f32_16x16x32_bf16 v[86:89], v[170:173], v[214:217], v[86:89]
	v_mfma_f32_16x16x32_bf16 v[82:85], v[182:185], v[214:217], v[82:85]
	s_setprio 0
	s_barrier
	s_add_i32 s30, s74, s29
	s_add_i32 m0, s30, 0xffffff80
	ds_read_b128 v[186:189], v147 offset:49152
	ds_read_b128 v[190:193], v147 offset:50176
	ds_read_b128 v[194:197], v147 offset:51200
	ds_read_b128 v[198:201], v147 offset:52224
	ds_read_b128 v[202:205], v147 offset:53248
	ds_read_b128 v[206:209], v147 offset:54272
	ds_read_b128 v[210:213], v147 offset:55296
	ds_read_b128 v[214:217], v147 offset:56320
	global_load_lds_dwordx4 v0, s[44:45] offset:128
	s_add_i32 m0, s30, 0x1f80
	s_add_u32 s30, s44, 0x80080
	s_addc_u32 s31, s45, 0
	s_add_i32 s44, s75, s29
	global_load_lds_dwordx4 v130, s[78:79] offset:128
	s_mov_b32 m0, s44
	s_nop 0
	global_load_lds_dwordx4 v0, s[30:31]
	s_add_i32 m0, s44, 0x2000
	s_nop 0
	global_load_lds_dwordx4 v130, s[30:31]
	s_add_i32 m0, s61, 0xffffff80
	s_nop 0
	global_load_lds_dwordx4 v136, s[46:47] offset:128
	s_add_i32 m0, s62, 0xffffff80
	s_nop 0
	global_load_lds_dwordx4 v132, s[46:47] offset:128
	s_waitcnt vmcnt(8)
	s_waitcnt lgkmcnt(0)
	s_barrier
	s_setprio 1
	s_waitcnt lgkmcnt(0)
	v_mfma_f32_16x16x32_bf16 v[102:105], v[148:151], v[186:189], v[102:105]
	v_mfma_f32_16x16x32_bf16 v[98:101], v[156:159], v[186:189], v[98:101]
	v_mfma_f32_16x16x32_bf16 v[126:129], v[148:151], v[194:197], v[126:129]
	v_mfma_f32_16x16x32_bf16 v[122:125], v[156:159], v[194:197], v[122:125]
	v_mfma_f32_16x16x32_bf16 v[94:97], v[148:151], v[202:205], v[94:97]
	v_mfma_f32_16x16x32_bf16 v[90:93], v[156:159], v[202:205], v[90:93]
	v_mfma_f32_16x16x32_bf16 v[54:57], v[148:151], v[210:213], v[54:57]
	v_mfma_f32_16x16x32_bf16 v[50:53], v[156:159], v[210:213], v[50:53]
	v_mfma_f32_16x16x32_bf16 v[102:105], v[152:155], v[190:193], v[102:105]
	v_mfma_f32_16x16x32_bf16 v[98:101], v[160:163], v[190:193], v[98:101]
	v_mfma_f32_16x16x32_bf16 v[126:129], v[152:155], v[198:201], v[126:129]
	v_mfma_f32_16x16x32_bf16 v[122:125], v[160:163], v[198:201], v[122:125]
	v_mfma_f32_16x16x32_bf16 v[94:97], v[152:155], v[206:209], v[94:97]
	v_mfma_f32_16x16x32_bf16 v[90:93], v[160:163], v[206:209], v[90:93]
	v_mfma_f32_16x16x32_bf16 v[54:57], v[152:155], v[214:217], v[54:57]
	v_mfma_f32_16x16x32_bf16 v[50:53], v[160:163], v[214:217], v[50:53]
	s_setprio 0
	s_setprio 1
	v_mfma_f32_16x16x32_bf16 v[118:121], v[164:167], v[186:189], v[118:121]
	v_mfma_f32_16x16x32_bf16 v[114:117], v[178:181], v[186:189], v[114:117]
	v_mfma_f32_16x16x32_bf16 v[110:113], v[164:167], v[194:197], v[110:113]
	v_mfma_f32_16x16x32_bf16 v[106:109], v[178:181], v[194:197], v[106:109]
	v_mfma_f32_16x16x32_bf16 v[70:73], v[164:167], v[202:205], v[70:73]
	v_mfma_f32_16x16x32_bf16 v[66:69], v[178:181], v[202:205], v[66:69]
	v_mfma_f32_16x16x32_bf16 v[38:41], v[164:167], v[210:213], v[38:41]
	v_mfma_f32_16x16x32_bf16 v[34:37], v[178:181], v[210:213], v[34:37]
	v_mfma_f32_16x16x32_bf16 v[118:121], v[170:173], v[190:193], v[118:121]
	v_mfma_f32_16x16x32_bf16 v[114:117], v[182:185], v[190:193], v[114:117]
	v_mfma_f32_16x16x32_bf16 v[110:113], v[170:173], v[198:201], v[110:113]
	v_mfma_f32_16x16x32_bf16 v[106:109], v[182:185], v[198:201], v[106:109]
	v_mfma_f32_16x16x32_bf16 v[70:73], v[170:173], v[206:209], v[70:73]
	v_mfma_f32_16x16x32_bf16 v[66:69], v[182:185], v[206:209], v[66:69]
	v_mfma_f32_16x16x32_bf16 v[38:41], v[170:173], v[214:217], v[38:41]
	v_mfma_f32_16x16x32_bf16 v[34:37], v[182:185], v[214:217], v[34:37]
	s_setprio 0
	s_barrier
	s_add_i32 s73, s73, 2
	s_add_u32 s42, s42, 0x100
	s_addc_u32 s43, s43, 0
	s_cmp_gt_u32 s73, 29
	s_cbranch_scc0 .LBB0_658
	s_add_u32 s42, s65, 0xffffff00
	s_addc_u32 s43, s68, -1
	s_andn2_b64 vcc, exec, s[40:41]
	s_cbranch_vccnz .LBB0_649
	v_mov_b32_e32 v34, 0
	s_mov_b32 s0, s14
	s_mov_b32 s50, s16
	s_mov_b64 s[12:13], s[22:23]
	s_mov_b32 s63, s64
	v_mov_b32_e32 v35, v34
	v_mov_b32_e32 v36, v34
	v_mov_b32_e32 v37, v34
	v_mov_b32_e32 v38, v34
	v_mov_b32_e32 v39, v34
	v_mov_b32_e32 v40, v34
	v_mov_b32_e32 v41, v34
	v_mov_b32_e32 v66, v34
	v_mov_b32_e32 v67, v34
	v_mov_b32_e32 v68, v34
	v_mov_b32_e32 v69, v34
	v_mov_b32_e32 v70, v34
	v_mov_b32_e32 v71, v34
	v_mov_b32_e32 v72, v34
	v_mov_b32_e32 v73, v34
	v_mov_b32_e32 v106, v34
	v_mov_b32_e32 v107, v34
	v_mov_b32_e32 v108, v34
	v_mov_b32_e32 v109, v34
	v_mov_b32_e32 v110, v34
	v_mov_b32_e32 v111, v34
	v_mov_b32_e32 v112, v34
	v_mov_b32_e32 v113, v34
	v_mov_b32_e32 v114, v34
	v_mov_b32_e32 v115, v34
	v_mov_b32_e32 v116, v34
	v_mov_b32_e32 v117, v34
	v_mov_b32_e32 v118, v34
	v_mov_b32_e32 v119, v34
	v_mov_b32_e32 v120, v34
	v_mov_b32_e32 v121, v34
	v_mov_b32_e32 v50, v34
	v_mov_b32_e32 v51, v34
	v_mov_b32_e32 v52, v34
	v_mov_b32_e32 v53, v34
	v_mov_b32_e32 v54, v34
	v_mov_b32_e32 v55, v34
	v_mov_b32_e32 v56, v34
	v_mov_b32_e32 v57, v34
	v_mov_b32_e32 v90, v34
	v_mov_b32_e32 v91, v34
	v_mov_b32_e32 v92, v34
	v_mov_b32_e32 v93, v34
	v_mov_b32_e32 v94, v34
	v_mov_b32_e32 v95, v34
	v_mov_b32_e32 v96, v34
	v_mov_b32_e32 v97, v34
	v_mov_b32_e32 v122, v34
	v_mov_b32_e32 v123, v34
	v_mov_b32_e32 v124, v34
	v_mov_b32_e32 v125, v34
	v_mov_b32_e32 v126, v34
	v_mov_b32_e32 v127, v34
	v_mov_b32_e32 v128, v34
	v_mov_b32_e32 v129, v34
	v_mov_b32_e32 v98, v34
	v_mov_b32_e32 v99, v34
	v_mov_b32_e32 v100, v34
	v_mov_b32_e32 v101, v34
	v_mov_b32_e32 v102, v34
	v_mov_b32_e32 v103, v34
	v_mov_b32_e32 v104, v34
	v_mov_b32_e32 v105, v34
	v_mov_b32_e32 v82, v34
	v_mov_b32_e32 v83, v34
	v_mov_b32_e32 v84, v34
	v_mov_b32_e32 v85, v34
	v_mov_b32_e32 v86, v34
	v_mov_b32_e32 v87, v34
	v_mov_b32_e32 v88, v34
	v_mov_b32_e32 v89, v34
	v_mov_b32_e32 v58, v34
	v_mov_b32_e32 v59, v34
	v_mov_b32_e32 v60, v34
	v_mov_b32_e32 v61, v34
	v_mov_b32_e32 v62, v34
	v_mov_b32_e32 v63, v34
	v_mov_b32_e32 v64, v34
	v_mov_b32_e32 v65, v34
	v_mov_b32_e32 v18, v34
	v_mov_b32_e32 v19, v34
	v_mov_b32_e32 v20, v34
	v_mov_b32_e32 v21, v34
	v_mov_b32_e32 v22, v34
	v_mov_b32_e32 v23, v34
	v_mov_b32_e32 v24, v34
	v_mov_b32_e32 v25, v34
	v_mov_b32_e32 v26, v34
	v_mov_b32_e32 v27, v34
	v_mov_b32_e32 v28, v34
	v_mov_b32_e32 v29, v34
	v_mov_b32_e32 v30, v34
	v_mov_b32_e32 v31, v34
	v_mov_b32_e32 v32, v34
	v_mov_b32_e32 v33, v34
	v_mov_b32_e32 v74, v34
	v_mov_b32_e32 v75, v34
	v_mov_b32_e32 v76, v34
	v_mov_b32_e32 v77, v34
	v_mov_b32_e32 v78, v34
	v_mov_b32_e32 v79, v34
	v_mov_b32_e32 v80, v34
	v_mov_b32_e32 v81, v34
	v_mov_b32_e32 v42, v34
	v_mov_b32_e32 v43, v34
	v_mov_b32_e32 v44, v34
	v_mov_b32_e32 v45, v34
	v_mov_b32_e32 v46, v34
	v_mov_b32_e32 v47, v34
	v_mov_b32_e32 v48, v34
	v_mov_b32_e32 v49, v34
	v_mov_b32_e32 v2, v34
	v_mov_b32_e32 v3, v34
	v_mov_b32_e32 v4, v34
	v_mov_b32_e32 v5, v34
	v_mov_b32_e32 v6, v34
	v_mov_b32_e32 v7, v34
	v_mov_b32_e32 v8, v34
	v_mov_b32_e32 v9, v34
	v_mov_b32_e32 v10, v34
	v_mov_b32_e32 v11, v34
	v_mov_b32_e32 v12, v34
	v_mov_b32_e32 v13, v34
	v_mov_b32_e32 v14, v34
	v_mov_b32_e32 v15, v34
	v_mov_b32_e32 v16, v34
	v_mov_b32_e32 v17, v34
	s_andn2_b64 vcc, exec, s[38:39]
	s_cbranch_vccnz .LBB0_650

.LBB0_764:
	s_add_u32 s64, s62, 0x100
	s_addc_u32 s65, s63, 0
	s_add_i32 s30, 0, 0x10000
	s_cmp_eq_u32 s81, 28
	s_cselect_b32 s75, s51, s65
	s_cselect_b32 s74, s77, s64
	s_cselect_b32 s73, s49, s80
	s_cselect_b32 s72, s78, s79
	s_add_i32 s82, 0, 0x14000
	v_add_u32_e32 v142, s30, v220
	v_add_u32_e32 v158, s82, v220
	ds_read_b128 v[130:133], v142
	ds_read_b128 v[134:137], v142 offset:1024
	ds_read_b128 v[138:141], v142 offset:2048
	ds_read_b128 v[142:145], v142 offset:3072
	ds_read_b128 v[146:149], v158
	ds_read_b128 v[150:153], v158 offset:1024
	ds_read_b128 v[154:157], v158 offset:2048
	ds_read_b128 v[158:161], v158 offset:3072
	s_add_i32 m0, s9, 0xc000
	ds_read_b128 v[162:165], v222
	ds_read_b128 v[170:173], v222 offset:1024
	ds_read_b128 v[184:187], v222 offset:2048
	ds_read_b128 v[188:191], v222 offset:3072
	ds_read_b128 v[192:195], v222 offset:4096
	ds_read_b128 v[196:199], v222 offset:5120
	ds_read_b128 v[200:203], v222 offset:6144
	ds_read_b128 v[204:207], v222 offset:7168
	global_load_lds_dwordx4 v182, s[62:63]
	s_add_i32 m0, s9, 0xe000
	s_nop 0
	global_load_lds_dwordx4 v180, s[62:63]
	s_waitcnt vmcnt(8)
	s_waitcnt lgkmcnt(0)
	s_barrier
	s_setprio 1
	s_waitcnt lgkmcnt(0)
	v_mfma_f32_16x16x32_bf16 v[94:97], v[130:133], v[162:165], v[94:97]
	v_mfma_f32_16x16x32_bf16 v[126:129], v[138:141], v[162:165], v[126:129]
	v_mfma_f32_16x16x32_bf16 v[90:93], v[130:133], v[184:187], v[90:93]
	v_mfma_f32_16x16x32_bf16 v[122:125], v[138:141], v[184:187], v[122:125]
	v_mfma_f32_16x16x32_bf16 v[86:89], v[130:133], v[192:195], v[86:89]
	v_mfma_f32_16x16x32_bf16 v[118:121], v[138:141], v[192:195], v[118:121]
	v_mfma_f32_16x16x32_bf16 v[82:85], v[130:133], v[200:203], v[82:85]
	v_mfma_f32_16x16x32_bf16 v[114:117], v[138:141], v[200:203], v[114:117]
	v_mfma_f32_16x16x32_bf16 v[94:97], v[134:137], v[170:173], v[94:97]
	v_mfma_f32_16x16x32_bf16 v[126:129], v[142:145], v[170:173], v[126:129]
	v_mfma_f32_16x16x32_bf16 v[90:93], v[134:137], v[188:191], v[90:93]
	v_mfma_f32_16x16x32_bf16 v[122:125], v[142:145], v[188:191], v[122:125]
	v_mfma_f32_16x16x32_bf16 v[86:89], v[134:137], v[196:199], v[86:89]
	v_mfma_f32_16x16x32_bf16 v[118:121], v[142:145], v[196:199], v[118:121]
	v_mfma_f32_16x16x32_bf16 v[82:85], v[134:137], v[204:207], v[82:85]
	v_mfma_f32_16x16x32_bf16 v[114:117], v[142:145], v[204:207], v[114:117]
	s_setprio 0
	s_setprio 1
	v_mfma_f32_16x16x32_bf16 v[78:81], v[146:149], v[162:165], v[78:81]
	v_mfma_f32_16x16x32_bf16 v[110:113], v[154:157], v[162:165], v[110:113]
	v_mfma_f32_16x16x32_bf16 v[74:77], v[146:149], v[184:187], v[74:77]
	v_mfma_f32_16x16x32_bf16 v[106:109], v[154:157], v[184:187], v[106:109]
	v_mfma_f32_16x16x32_bf16 v[70:73], v[146:149], v[192:195], v[70:73]
	v_mfma_f32_16x16x32_bf16 v[102:105], v[154:157], v[192:195], v[102:105]
	v_mfma_f32_16x16x32_bf16 v[66:69], v[146:149], v[200:203], v[66:69]
	v_mfma_f32_16x16x32_bf16 v[98:101], v[154:157], v[200:203], v[98:101]
	v_mfma_f32_16x16x32_bf16 v[78:81], v[150:153], v[170:173], v[78:81]
	v_mfma_f32_16x16x32_bf16 v[110:113], v[158:161], v[170:173], v[110:113]
	v_mfma_f32_16x16x32_bf16 v[74:77], v[150:153], v[188:191], v[74:77]
	v_mfma_f32_16x16x32_bf16 v[106:109], v[158:161], v[188:191], v[106:109]
	v_mfma_f32_16x16x32_bf16 v[70:73], v[150:153], v[196:199], v[70:73]
	v_mfma_f32_16x16x32_bf16 v[102:105], v[158:161], v[196:199], v[102:105]
	v_mfma_f32_16x16x32_bf16 v[66:69], v[150:153], v[204:207], v[66:69]
	v_mfma_f32_16x16x32_bf16 v[98:101], v[158:161], v[204:207], v[98:101]
	s_setprio 0
	s_barrier
	s_add_i32 s30, s30, s8
	s_mov_b32 m0, s30
	ds_read_b128 v[162:165], v222 offset:16384
	ds_read_b128 v[170:173], v222 offset:17408
	ds_read_b128 v[184:187], v222 offset:18432
	ds_read_b128 v[188:191], v222 offset:19456
	ds_read_b128 v[192:195], v222 offset:20480
	ds_read_b128 v[196:199], v222 offset:21504
	ds_read_b128 v[200:203], v222 offset:22528
	ds_read_b128 v[204:207], v222 offset:23552
	global_load_lds_dwordx4 v0, s[72:73]
	s_add_i32 m0, s30, 0x2000
	s_add_u32 s30, s72, 0x80000
	s_addc_u32 s31, s73, 0
	s_add_i32 s62, s82, s8
	global_load_lds_dwordx4 v174, s[72:73]
	s_mov_b32 m0, s62
	s_nop 0
	global_load_lds_dwordx4 v0, s[30:31]
	s_add_i32 m0, s62, 0x2000
	s_nop 0
	global_load_lds_dwordx4 v174, s[30:31]
	s_mov_b32 m0, s9
	s_nop 0
	global_load_lds_dwordx4 v178, s[74:75]
	s_mov_b32 m0, s18
	s_nop 0
	global_load_lds_dwordx4 v176, s[74:75]
	s_waitcnt vmcnt(8)
	s_waitcnt lgkmcnt(0)
	s_barrier
	s_setprio 1
	s_waitcnt lgkmcnt(0)
	v_mfma_f32_16x16x32_bf16 v[10:13], v[130:133], v[162:165], v[10:13]
	v_mfma_f32_16x16x32_bf16 v[42:45], v[138:141], v[162:165], v[42:45]
	v_mfma_f32_16x16x32_bf16 v[18:21], v[130:133], v[184:187], v[18:21]
	v_mfma_f32_16x16x32_bf16 v[50:53], v[138:141], v[184:187], v[50:53]
	v_mfma_f32_16x16x32_bf16 v[26:29], v[130:133], v[192:195], v[26:29]
	v_mfma_f32_16x16x32_bf16 v[58:61], v[138:141], v[192:195], v[58:61]
	v_mfma_f32_16x16x32_bf16 v[30:33], v[130:133], v[200:203], v[30:33]
	v_mfma_f32_16x16x32_bf16 v[62:65], v[138:141], v[200:203], v[62:65]
	v_mfma_f32_16x16x32_bf16 v[10:13], v[134:137], v[170:173], v[10:13]
	v_mfma_f32_16x16x32_bf16 v[42:45], v[142:145], v[170:173], v[42:45]
	v_mfma_f32_16x16x32_bf16 v[18:21], v[134:137], v[188:191], v[18:21]
	v_mfma_f32_16x16x32_bf16 v[50:53], v[142:145], v[188:191], v[50:53]
	v_mfma_f32_16x16x32_bf16 v[26:29], v[134:137], v[196:199], v[26:29]
	v_mfma_f32_16x16x32_bf16 v[58:61], v[142:145], v[196:199], v[58:61]
	v_mfma_f32_16x16x32_bf16 v[30:33], v[134:137], v[204:207], v[30:33]
	v_mfma_f32_16x16x32_bf16 v[62:65], v[142:145], v[204:207], v[62:65]
	s_setprio 0
	s_setprio 1
	v_mfma_f32_16x16x32_bf16 v[2:5], v[146:149], v[162:165], v[2:5]
	v_mfma_f32_16x16x32_bf16 v[34:37], v[154:157], v[162:165], v[34:37]
	v_mfma_f32_16x16x32_bf16 v[6:9], v[146:149], v[184:187], v[6:9]
	v_mfma_f32_16x16x32_bf16 v[38:41], v[154:157], v[184:187], v[38:41]
	v_mfma_f32_16x16x32_bf16 v[14:17], v[146:149], v[192:195], v[14:17]
	v_mfma_f32_16x16x32_bf16 v[46:49], v[154:157], v[192:195], v[46:49]
	v_mfma_f32_16x16x32_bf16 v[22:25], v[146:149], v[200:203], v[22:25]
	v_mfma_f32_16x16x32_bf16 v[54:57], v[154:157], v[200:203], v[54:57]
	v_mfma_f32_16x16x32_bf16 v[2:5], v[150:153], v[170:173], v[2:5]
	v_mfma_f32_16x16x32_bf16 v[34:37], v[158:161], v[170:173], v[34:37]
	v_mfma_f32_16x16x32_bf16 v[6:9], v[150:153], v[188:191], v[6:9]
	v_mfma_f32_16x16x32_bf16 v[38:41], v[158:161], v[188:191], v[38:41]
	v_mfma_f32_16x16x32_bf16 v[14:17], v[150:153], v[196:199], v[14:17]
	v_mfma_f32_16x16x32_bf16 v[46:49], v[158:161], v[196:199], v[46:49]
	v_mfma_f32_16x16x32_bf16 v[22:25], v[150:153], v[204:207], v[22:25]
	v_mfma_f32_16x16x32_bf16 v[54:57], v[158:161], v[204:207], v[54:57]
	s_setprio 0
	s_barrier
	s_add_i32 s62, 0, 0x18000
	s_add_i32 s63, 0, 0x1c000
	v_add_u32_e32 v142, s62, v220
	v_add_u32_e32 v158, s63, v220
	ds_read_b128 v[130:133], v142
	ds_read_b128 v[134:137], v142 offset:1024
	ds_read_b128 v[138:141], v142 offset:2048
	ds_read_b128 v[142:145], v142 offset:3072
	ds_read_b128 v[146:149], v158
	ds_read_b128 v[150:153], v158 offset:1024
	ds_read_b128 v[154:157], v158 offset:2048
	ds_read_b128 v[158:161], v158 offset:3072
	s_add_u32 s30, s74, 0x80000
	s_addc_u32 s31, s75, 0
	s_mov_b32 m0, s28
	ds_read_b128 v[162:165], v222 offset:32768
	ds_read_b128 v[170:173], v222 offset:33792
	ds_read_b128 v[184:187], v222 offset:34816
	ds_read_b128 v[188:191], v222 offset:35840
	ds_read_b128 v[192:195], v222 offset:36864
	ds_read_b128 v[196:199], v222 offset:37888
	ds_read_b128 v[200:203], v222 offset:38912
	ds_read_b128 v[204:207], v222 offset:39936
	global_load_lds_dwordx4 v178, s[30:31]
	s_mov_b32 m0, s29
	s_nop 0
	global_load_lds_dwordx4 v176, s[30:31]
	s_waitcnt vmcnt(8)
	s_waitcnt lgkmcnt(0)
	s_barrier
	s_setprio 1
	s_waitcnt lgkmcnt(0)
	v_mfma_f32_16x16x32_bf16 v[94:97], v[130:133], v[162:165], v[94:97]
	v_mfma_f32_16x16x32_bf16 v[126:129], v[138:141], v[162:165], v[126:129]
	v_mfma_f32_16x16x32_bf16 v[90:93], v[130:133], v[184:187], v[90:93]
	v_mfma_f32_16x16x32_bf16 v[122:125], v[138:141], v[184:187], v[122:125]
	v_mfma_f32_16x16x32_bf16 v[86:89], v[130:133], v[192:195], v[86:89]
	v_mfma_f32_16x16x32_bf16 v[118:121], v[138:141], v[192:195], v[118:121]
	v_mfma_f32_16x16x32_bf16 v[82:85], v[130:133], v[200:203], v[82:85]
	v_mfma_f32_16x16x32_bf16 v[114:117], v[138:141], v[200:203], v[114:117]
	v_mfma_f32_16x16x32_bf16 v[94:97], v[134:137], v[170:173], v[94:97]
	v_mfma_f32_16x16x32_bf16 v[126:129], v[142:145], v[170:173], v[126:129]
	v_mfma_f32_16x16x32_bf16 v[90:93], v[134:137], v[188:191], v[90:93]
	v_mfma_f32_16x16x32_bf16 v[122:125], v[142:145], v[188:191], v[122:125]
	v_mfma_f32_16x16x32_bf16 v[86:89], v[134:137], v[196:199], v[86:89]
	v_mfma_f32_16x16x32_bf16 v[118:121], v[142:145], v[196:199], v[118:121]
	v_mfma_f32_16x16x32_bf16 v[82:85], v[134:137], v[204:207], v[82:85]
	v_mfma_f32_16x16x32_bf16 v[114:117], v[142:145], v[204:207], v[114:117]
	s_setprio 0
	s_setprio 1
	v_mfma_f32_16x16x32_bf16 v[78:81], v[146:149], v[162:165], v[78:81]
	v_mfma_f32_16x16x32_bf16 v[110:113], v[154:157], v[162:165], v[110:113]
	v_mfma_f32_16x16x32_bf16 v[74:77], v[146:149], v[184:187], v[74:77]
	v_mfma_f32_16x16x32_bf16 v[106:109], v[154:157], v[184:187], v[106:109]
	v_mfma_f32_16x16x32_bf16 v[70:73], v[146:149], v[192:195], v[70:73]
	v_mfma_f32_16x16x32_bf16 v[102:105], v[154:157], v[192:195], v[102:105]
	v_mfma_f32_16x16x32_bf16 v[66:69], v[146:149], v[200:203], v[66:69]
	v_mfma_f32_16x16x32_bf16 v[98:101], v[154:157], v[200:203], v[98:101]
	v_mfma_f32_16x16x32_bf16 v[78:81], v[150:153], v[170:173], v[78:81]
	v_mfma_f32_16x16x32_bf16 v[110:113], v[158:161], v[170:173], v[110:113]
	v_mfma_f32_16x16x32_bf16 v[74:77], v[150:153], v[188:191], v[74:77]
	v_mfma_f32_16x16x32_bf16 v[106:109], v[158:161], v[188:191], v[106:109]
	v_mfma_f32_16x16x32_bf16 v[70:73], v[150:153], v[196:199], v[70:73]
	v_mfma_f32_16x16x32_bf16 v[102:105], v[158:161], v[196:199], v[102:105]
	v_mfma_f32_16x16x32_bf16 v[66:69], v[150:153], v[204:207], v[66:69]
	v_mfma_f32_16x16x32_bf16 v[98:101], v[158:161], v[204:207], v[98:101]
	s_setprio 0
	s_barrier
	s_add_i32 s30, s62, s8
	s_add_i32 m0, s30, 0xffffff80
	ds_read_b128 v[162:165], v222 offset:49152
	ds_read_b128 v[170:173], v222 offset:50176
	ds_read_b128 v[184:187], v222 offset:51200
	ds_read_b128 v[188:191], v222 offset:52224
	ds_read_b128 v[192:195], v222 offset:53248
	ds_read_b128 v[196:199], v222 offset:54272
	ds_read_b128 v[200:203], v222 offset:55296
	ds_read_b128 v[204:207], v222 offset:56320
	global_load_lds_dwordx4 v0, s[72:73] offset:128
	s_add_i32 m0, s30, 0x1f80
	s_add_u32 s30, s72, 0x80080
	s_addc_u32 s31, s73, 0
	s_add_i32 s62, s63, s8
	global_load_lds_dwordx4 v174, s[72:73] offset:128
	s_mov_b32 m0, s62
	s_nop 0
	global_load_lds_dwordx4 v0, s[30:31]
	s_add_i32 m0, s62, 0x2000
	s_nop 0
	global_load_lds_dwordx4 v174, s[30:31]
	s_add_i32 m0, s54, 0xffffff80
	s_nop 0
	global_load_lds_dwordx4 v178, s[74:75] offset:128
	s_add_i32 m0, s55, 0xffffff80
	s_nop 0
	global_load_lds_dwordx4 v176, s[74:75] offset:128
	s_waitcnt vmcnt(8)
	s_waitcnt lgkmcnt(0)
	s_barrier
	s_setprio 1
	s_waitcnt lgkmcnt(0)
	v_mfma_f32_16x16x32_bf16 v[10:13], v[130:133], v[162:165], v[10:13]
	v_mfma_f32_16x16x32_bf16 v[42:45], v[138:141], v[162:165], v[42:45]
	v_mfma_f32_16x16x32_bf16 v[18:21], v[130:133], v[184:187], v[18:21]
	v_mfma_f32_16x16x32_bf16 v[50:53], v[138:141], v[184:187], v[50:53]
	v_mfma_f32_16x16x32_bf16 v[26:29], v[130:133], v[192:195], v[26:29]
	v_mfma_f32_16x16x32_bf16 v[58:61], v[138:141], v[192:195], v[58:61]
	v_mfma_f32_16x16x32_bf16 v[30:33], v[130:133], v[200:203], v[30:33]
	v_mfma_f32_16x16x32_bf16 v[62:65], v[138:141], v[200:203], v[62:65]
	v_mfma_f32_16x16x32_bf16 v[10:13], v[134:137], v[170:173], v[10:13]
	v_mfma_f32_16x16x32_bf16 v[42:45], v[142:145], v[170:173], v[42:45]
	v_mfma_f32_16x16x32_bf16 v[18:21], v[134:137], v[188:191], v[18:21]
	v_mfma_f32_16x16x32_bf16 v[50:53], v[142:145], v[188:191], v[50:53]
	v_mfma_f32_16x16x32_bf16 v[26:29], v[134:137], v[196:199], v[26:29]
	v_mfma_f32_16x16x32_bf16 v[58:61], v[142:145], v[196:199], v[58:61]
	v_mfma_f32_16x16x32_bf16 v[30:33], v[134:137], v[204:207], v[30:33]
	v_mfma_f32_16x16x32_bf16 v[62:65], v[142:145], v[204:207], v[62:65]
	s_setprio 0
	s_setprio 1
	v_mfma_f32_16x16x32_bf16 v[2:5], v[146:149], v[162:165], v[2:5]
	v_mfma_f32_16x16x32_bf16 v[34:37], v[154:157], v[162:165], v[34:37]
	v_mfma_f32_16x16x32_bf16 v[6:9], v[146:149], v[184:187], v[6:9]
	v_mfma_f32_16x16x32_bf16 v[38:41], v[154:157], v[184:187], v[38:41]
	v_mfma_f32_16x16x32_bf16 v[14:17], v[146:149], v[192:195], v[14:17]
	v_mfma_f32_16x16x32_bf16 v[46:49], v[154:157], v[192:195], v[46:49]
	v_mfma_f32_16x16x32_bf16 v[22:25], v[146:149], v[200:203], v[22:25]
	v_mfma_f32_16x16x32_bf16 v[54:57], v[154:157], v[200:203], v[54:57]
	v_mfma_f32_16x16x32_bf16 v[2:5], v[150:153], v[170:173], v[2:5]
	v_mfma_f32_16x16x32_bf16 v[34:37], v[158:161], v[170:173], v[34:37]
	v_mfma_f32_16x16x32_bf16 v[6:9], v[150:153], v[188:191], v[6:9]
	v_mfma_f32_16x16x32_bf16 v[38:41], v[158:161], v[188:191], v[38:41]
	v_mfma_f32_16x16x32_bf16 v[14:17], v[150:153], v[196:199], v[14:17]
	v_mfma_f32_16x16x32_bf16 v[46:49], v[158:161], v[196:199], v[46:49]
	v_mfma_f32_16x16x32_bf16 v[22:25], v[150:153], v[204:207], v[22:25]
	v_mfma_f32_16x16x32_bf16 v[54:57], v[158:161], v[204:207], v[54:57]
	s_setprio 0
	s_barrier
	s_add_i32 s81, s81, 2
	s_add_u32 s79, s79, 0x100
	s_addc_u32 s80, s80, 0
	s_cmp_gt_u32 s81, 29
	s_mov_b64 s[62:63], s[64:65]
	s_cbranch_scc0 .LBB0_764
	s_and_b64 vcc, exec, s[42:43]
	s_cbranch_vccz .LBB0_767
	s_barrier

.LBB0_966:
	s_add_u32 s30, s20, s40
	s_addc_u32 s31, s21, s41
	s_add_u32 s30, s30, 0x100
	s_addc_u32 s31, s31, 0
	s_add_u32 s42, s62, s40
	s_addc_u32 s43, s63, s41
	s_add_i32 s65, 0, 0x10000
	s_cmpk_eq_i32 s40, 0x2b00
	s_cselect_b32 s45, s23, s31
	s_cselect_b32 s44, s22, s30
	v_add_u32_e32 v147, s65, v145
	s_cselect_b32 s43, s1, s43
	s_cselect_b32 s42, s0, s42
	s_add_i32 s68, 0, 0x14000
	ds_read_b128 v[148:151], v147
	ds_read_b128 v[152:155], v147 offset:1024
	ds_read_b128 v[156:159], v147 offset:2048
	ds_read_b128 v[160:163], v147 offset:3072
	v_add_u32_e32 v147, s68, v145
	ds_read_b128 v[170:173], v147
	ds_read_b128 v[174:177], v147 offset:1024
	ds_read_b128 v[178:181], v147 offset:2048
	ds_read_b128 v[182:185], v147 offset:3072
	s_add_u32 s84, s20, s40
	s_addc_u32 s85, s21, s41
	s_add_u32 s84, s84, 0x160080
	s_addc_u32 s85, s85, 0
	s_add_i32 m0, s28, 0xc000
	ds_read_b128 v[186:189], v146
	ds_read_b128 v[190:193], v146 offset:1024
	ds_read_b128 v[194:197], v146 offset:2048
	ds_read_b128 v[200:203], v146 offset:3072
	ds_read_b128 v[204:207], v146 offset:4096
	ds_read_b128 v[208:211], v146 offset:5120
	ds_read_b128 v[212:215], v146 offset:6144
	ds_read_b128 v[216:219], v146 offset:7168
	global_load_lds_dwordx4 v138, s[84:85]
	s_add_i32 m0, s28, 0xe000
	s_nop 0
	global_load_lds_dwordx4 v136, s[84:85]
	s_waitcnt vmcnt(8)
	s_waitcnt lgkmcnt(0)
	s_barrier
	s_setprio 1
	s_waitcnt lgkmcnt(0)
	v_mfma_f32_16x16x32_bf16 v[128:131], v[148:151], v[186:189], v[128:131]
	v_mfma_f32_16x16x32_bf16 v[124:127], v[156:159], v[186:189], v[124:127]
	v_mfma_f32_16x16x32_bf16 v[120:123], v[148:151], v[194:197], v[120:123]
	v_mfma_f32_16x16x32_bf16 v[116:119], v[156:159], v[194:197], v[116:119]
	v_mfma_f32_16x16x32_bf16 v[108:111], v[148:151], v[204:207], v[108:111]
	v_mfma_f32_16x16x32_bf16 v[104:107], v[156:159], v[204:207], v[104:107]
	v_mfma_f32_16x16x32_bf16 v[100:103], v[148:151], v[212:215], v[100:103]
	v_mfma_f32_16x16x32_bf16 v[92:95], v[156:159], v[212:215], v[92:95]
	v_mfma_f32_16x16x32_bf16 v[128:131], v[152:155], v[190:193], v[128:131]
	v_mfma_f32_16x16x32_bf16 v[124:127], v[160:163], v[190:193], v[124:127]
	v_mfma_f32_16x16x32_bf16 v[120:123], v[152:155], v[200:203], v[120:123]
	v_mfma_f32_16x16x32_bf16 v[116:119], v[160:163], v[200:203], v[116:119]
	v_mfma_f32_16x16x32_bf16 v[108:111], v[152:155], v[208:211], v[108:111]
	v_mfma_f32_16x16x32_bf16 v[104:107], v[160:163], v[208:211], v[104:107]
	v_mfma_f32_16x16x32_bf16 v[100:103], v[152:155], v[216:219], v[100:103]
	v_mfma_f32_16x16x32_bf16 v[92:95], v[160:163], v[216:219], v[92:95]
	s_setprio 0
	s_setprio 1
	v_mfma_f32_16x16x32_bf16 v[112:115], v[170:173], v[186:189], v[112:115]
	v_mfma_f32_16x16x32_bf16 v[96:99], v[178:181], v[186:189], v[96:99]
	v_mfma_f32_16x16x32_bf16 v[76:79], v[170:173], v[194:197], v[76:79]
	v_mfma_f32_16x16x32_bf16 v[64:67], v[178:181], v[194:197], v[64:67]
	v_mfma_f32_16x16x32_bf16 v[68:71], v[170:173], v[204:207], v[68:71]
	v_mfma_f32_16x16x32_bf16 v[52:55], v[178:181], v[204:207], v[52:55]
	v_mfma_f32_16x16x32_bf16 v[56:59], v[170:173], v[212:215], v[56:59]
	v_mfma_f32_16x16x32_bf16 v[40:43], v[178:181], v[212:215], v[40:43]
	v_mfma_f32_16x16x32_bf16 v[112:115], v[174:177], v[190:193], v[112:115]
	v_mfma_f32_16x16x32_bf16 v[96:99], v[182:185], v[190:193], v[96:99]
	v_mfma_f32_16x16x32_bf16 v[76:79], v[174:177], v[200:203], v[76:79]
	v_mfma_f32_16x16x32_bf16 v[64:67], v[182:185], v[200:203], v[64:67]
	v_mfma_f32_16x16x32_bf16 v[68:71], v[174:177], v[208:211], v[68:71]
	v_mfma_f32_16x16x32_bf16 v[52:55], v[182:185], v[208:211], v[52:55]
	v_mfma_f32_16x16x32_bf16 v[56:59], v[174:177], v[216:219], v[56:59]
	v_mfma_f32_16x16x32_bf16 v[40:43], v[182:185], v[216:219], v[40:43]
	s_setprio 0
	s_barrier
	s_add_i32 s30, s65, s4
	s_mov_b32 m0, s30
	ds_read_b128 v[186:189], v146 offset:16384
	ds_read_b128 v[190:193], v146 offset:17408
	ds_read_b128 v[194:197], v146 offset:18432
	ds_read_b128 v[200:203], v146 offset:19456
	ds_read_b128 v[204:207], v146 offset:20480
	ds_read_b128 v[208:211], v146 offset:21504
	ds_read_b128 v[212:215], v146 offset:22528
	ds_read_b128 v[216:219], v146 offset:23552
	global_load_lds_dwordx4 v0, s[42:43]
	s_add_i32 m0, s30, 0x2000
	s_add_u32 s30, s42, 0x160000
	s_mov_b64 s[78:79], s[42:43]
	s_addc_u32 s31, s43, 0
	s_add_i32 s65, s68, s4
	global_load_lds_dwordx4 v30, s[42:43]
	s_mov_b32 m0, s65
	s_nop 0
	global_load_lds_dwordx4 v0, s[30:31]
	s_add_i32 m0, s65, 0x2000
	s_nop 0
	global_load_lds_dwordx4 v30, s[30:31]
	s_mov_b32 m0, s28
	s_nop 0
	global_load_lds_dwordx4 v134, s[44:45]
	s_mov_b32 m0, s29
	s_nop 0
	global_load_lds_dwordx4 v132, s[44:45]
	s_waitcnt vmcnt(8)
	s_waitcnt lgkmcnt(0)
	s_barrier
	s_setprio 1
	s_waitcnt lgkmcnt(0)
	v_mfma_f32_16x16x32_bf16 v[88:91], v[148:151], v[186:189], v[88:91]
	v_mfma_f32_16x16x32_bf16 v[84:87], v[156:159], v[186:189], v[84:87]
	v_mfma_f32_16x16x32_bf16 v[80:83], v[148:151], v[194:197], v[80:83]
	v_mfma_f32_16x16x32_bf16 v[72:75], v[156:159], v[194:197], v[72:75]
	v_mfma_f32_16x16x32_bf16 v[60:63], v[148:151], v[204:207], v[60:63]
	v_mfma_f32_16x16x32_bf16 v[48:51], v[156:159], v[204:207], v[48:51]
	v_mfma_f32_16x16x32_bf16 v[36:39], v[148:151], v[212:215], v[36:39]
	v_mfma_f32_16x16x32_bf16 v[32:35], v[156:159], v[212:215], v[32:35]
	v_mfma_f32_16x16x32_bf16 v[88:91], v[152:155], v[190:193], v[88:91]
	v_mfma_f32_16x16x32_bf16 v[84:87], v[160:163], v[190:193], v[84:87]
	v_mfma_f32_16x16x32_bf16 v[80:83], v[152:155], v[200:203], v[80:83]
	v_mfma_f32_16x16x32_bf16 v[72:75], v[160:163], v[200:203], v[72:75]
	v_mfma_f32_16x16x32_bf16 v[60:63], v[152:155], v[208:211], v[60:63]
	v_mfma_f32_16x16x32_bf16 v[48:51], v[160:163], v[208:211], v[48:51]
	v_mfma_f32_16x16x32_bf16 v[36:39], v[152:155], v[216:219], v[36:39]
	v_mfma_f32_16x16x32_bf16 v[32:35], v[160:163], v[216:219], v[32:35]
	s_setprio 0
	s_setprio 1
	v_mfma_f32_16x16x32_bf16 v[44:47], v[170:173], v[186:189], v[44:47]
	v_mfma_f32_16x16x32_bf16 v[26:29], v[178:181], v[186:189], v[26:29]
	v_mfma_f32_16x16x32_bf16 v[22:25], v[170:173], v[194:197], v[22:25]
	v_mfma_f32_16x16x32_bf16 v[18:21], v[178:181], v[194:197], v[18:21]
	v_mfma_f32_16x16x32_bf16 v[14:17], v[170:173], v[204:207], v[14:17]
	v_mfma_f32_16x16x32_bf16 v[10:13], v[178:181], v[204:207], v[10:13]
	v_mfma_f32_16x16x32_bf16 v[6:9], v[170:173], v[212:215], v[6:9]
	v_mfma_f32_16x16x32_bf16 v[2:5], v[178:181], v[212:215], v[2:5]
	v_mfma_f32_16x16x32_bf16 v[44:47], v[174:177], v[190:193], v[44:47]
	v_mfma_f32_16x16x32_bf16 v[26:29], v[182:185], v[190:193], v[26:29]
	v_mfma_f32_16x16x32_bf16 v[22:25], v[174:177], v[200:203], v[22:25]
	v_mfma_f32_16x16x32_bf16 v[18:21], v[182:185], v[200:203], v[18:21]
	v_mfma_f32_16x16x32_bf16 v[14:17], v[174:177], v[208:211], v[14:17]
	v_mfma_f32_16x16x32_bf16 v[10:13], v[182:185], v[208:211], v[10:13]
	v_mfma_f32_16x16x32_bf16 v[6:9], v[174:177], v[216:219], v[6:9]
	v_mfma_f32_16x16x32_bf16 v[2:5], v[182:185], v[216:219], v[2:5]
	s_setprio 0
	s_barrier
	s_add_i32 s65, 0, 0x18000
	v_add_u32_e32 v147, s65, v145
	s_add_i32 s68, 0, 0x1c000
	ds_read_b128 v[148:151], v147
	ds_read_b128 v[152:155], v147 offset:1024
	ds_read_b128 v[156:159], v147 offset:2048
	ds_read_b128 v[160:163], v147 offset:3072
	v_add_u32_e32 v147, s68, v145
	ds_read_b128 v[170:173], v147
	ds_read_b128 v[174:177], v147 offset:1024
	ds_read_b128 v[178:181], v147 offset:2048
	ds_read_b128 v[182:185], v147 offset:3072
	s_add_u32 s30, s44, 0x160000
	s_addc_u32 s31, s45, 0
	s_mov_b32 m0, s49
	ds_read_b128 v[186:189], v146 offset:32768
	ds_read_b128 v[190:193], v146 offset:33792
	ds_read_b128 v[194:197], v146 offset:34816
	ds_read_b128 v[200:203], v146 offset:35840
	ds_read_b128 v[204:207], v146 offset:36864
	ds_read_b128 v[208:211], v146 offset:37888
	ds_read_b128 v[212:215], v146 offset:38912
	ds_read_b128 v[216:219], v146 offset:39936
	global_load_lds_dwordx4 v134, s[30:31]
	s_mov_b32 m0, s50
	s_nop 0
	global_load_lds_dwordx4 v132, s[30:31]
	s_waitcnt vmcnt(8)
	s_waitcnt lgkmcnt(0)
	s_barrier
	s_setprio 1
	s_waitcnt lgkmcnt(0)
	v_mfma_f32_16x16x32_bf16 v[128:131], v[148:151], v[186:189], v[128:131]
	v_mfma_f32_16x16x32_bf16 v[124:127], v[156:159], v[186:189], v[124:127]
	v_mfma_f32_16x16x32_bf16 v[120:123], v[148:151], v[194:197], v[120:123]
	v_mfma_f32_16x16x32_bf16 v[116:119], v[156:159], v[194:197], v[116:119]
	v_mfma_f32_16x16x32_bf16 v[108:111], v[148:151], v[204:207], v[108:111]
	v_mfma_f32_16x16x32_bf16 v[104:107], v[156:159], v[204:207], v[104:107]
	v_mfma_f32_16x16x32_bf16 v[100:103], v[148:151], v[212:215], v[100:103]
	v_mfma_f32_16x16x32_bf16 v[92:95], v[156:159], v[212:215], v[92:95]
	v_mfma_f32_16x16x32_bf16 v[128:131], v[152:155], v[190:193], v[128:131]
	v_mfma_f32_16x16x32_bf16 v[124:127], v[160:163], v[190:193], v[124:127]
	v_mfma_f32_16x16x32_bf16 v[120:123], v[152:155], v[200:203], v[120:123]
	v_mfma_f32_16x16x32_bf16 v[116:119], v[160:163], v[200:203], v[116:119]
	v_mfma_f32_16x16x32_bf16 v[108:111], v[152:155], v[208:211], v[108:111]
	v_mfma_f32_16x16x32_bf16 v[104:107], v[160:163], v[208:211], v[104:107]
	v_mfma_f32_16x16x32_bf16 v[100:103], v[152:155], v[216:219], v[100:103]
	v_mfma_f32_16x16x32_bf16 v[92:95], v[160:163], v[216:219], v[92:95]
	s_setprio 0
	s_setprio 1
	v_mfma_f32_16x16x32_bf16 v[112:115], v[170:173], v[186:189], v[112:115]
	v_mfma_f32_16x16x32_bf16 v[96:99], v[178:181], v[186:189], v[96:99]
	v_mfma_f32_16x16x32_bf16 v[76:79], v[170:173], v[194:197], v[76:79]
	v_mfma_f32_16x16x32_bf16 v[64:67], v[178:181], v[194:197], v[64:67]
	v_mfma_f32_16x16x32_bf16 v[68:71], v[170:173], v[204:207], v[68:71]
	v_mfma_f32_16x16x32_bf16 v[52:55], v[178:181], v[204:207], v[52:55]
	v_mfma_f32_16x16x32_bf16 v[56:59], v[170:173], v[212:215], v[56:59]
	v_mfma_f32_16x16x32_bf16 v[40:43], v[178:181], v[212:215], v[40:43]
	v_mfma_f32_16x16x32_bf16 v[112:115], v[174:177], v[190:193], v[112:115]
	v_mfma_f32_16x16x32_bf16 v[96:99], v[182:185], v[190:193], v[96:99]
	v_mfma_f32_16x16x32_bf16 v[76:79], v[174:177], v[200:203], v[76:79]
	v_mfma_f32_16x16x32_bf16 v[64:67], v[182:185], v[200:203], v[64:67]
	v_mfma_f32_16x16x32_bf16 v[68:71], v[174:177], v[208:211], v[68:71]
	v_mfma_f32_16x16x32_bf16 v[52:55], v[182:185], v[208:211], v[52:55]
	v_mfma_f32_16x16x32_bf16 v[56:59], v[174:177], v[216:219], v[56:59]
	v_mfma_f32_16x16x32_bf16 v[40:43], v[182:185], v[216:219], v[40:43]
	s_setprio 0
	s_barrier
	s_add_i32 s30, s65, s4
	s_add_i32 m0, s30, 0xffffff80
	ds_read_b128 v[186:189], v146 offset:49152
	ds_read_b128 v[190:193], v146 offset:50176
	ds_read_b128 v[194:197], v146 offset:51200
	ds_read_b128 v[200:203], v146 offset:52224
	ds_read_b128 v[204:207], v146 offset:53248
	ds_read_b128 v[208:211], v146 offset:54272
	ds_read_b128 v[212:215], v146 offset:55296
	ds_read_b128 v[216:219], v146 offset:56320
	global_load_lds_dwordx4 v0, s[42:43] offset:128
	s_add_i32 m0, s30, 0x1f80
	s_add_u32 s30, s42, 0x160080
	s_addc_u32 s31, s43, 0
	s_add_i32 s42, s68, s4
	global_load_lds_dwordx4 v30, s[78:79] offset:128
	s_mov_b32 m0, s42
	s_nop 0
	global_load_lds_dwordx4 v0, s[30:31]
	s_add_i32 m0, s42, 0x2000
	s_nop 0
	global_load_lds_dwordx4 v30, s[30:31]
	s_add_i32 m0, s52, 0xffffff80
	s_nop 0
	global_load_lds_dwordx4 v134, s[44:45] offset:128
	s_add_i32 m0, s53, 0xffffff80
	s_nop 0
	global_load_lds_dwordx4 v132, s[44:45] offset:128
	s_waitcnt vmcnt(8)
	s_waitcnt lgkmcnt(0)
	s_barrier
	s_setprio 1
	s_waitcnt lgkmcnt(0)
	v_mfma_f32_16x16x32_bf16 v[88:91], v[148:151], v[186:189], v[88:91]
	v_mfma_f32_16x16x32_bf16 v[84:87], v[156:159], v[186:189], v[84:87]
	v_mfma_f32_16x16x32_bf16 v[80:83], v[148:151], v[194:197], v[80:83]
	v_mfma_f32_16x16x32_bf16 v[72:75], v[156:159], v[194:197], v[72:75]
	v_mfma_f32_16x16x32_bf16 v[60:63], v[148:151], v[204:207], v[60:63]
	v_mfma_f32_16x16x32_bf16 v[48:51], v[156:159], v[204:207], v[48:51]
	v_mfma_f32_16x16x32_bf16 v[36:39], v[148:151], v[212:215], v[36:39]
	v_mfma_f32_16x16x32_bf16 v[32:35], v[156:159], v[212:215], v[32:35]
	v_mfma_f32_16x16x32_bf16 v[88:91], v[152:155], v[190:193], v[88:91]
	v_mfma_f32_16x16x32_bf16 v[84:87], v[160:163], v[190:193], v[84:87]
	v_mfma_f32_16x16x32_bf16 v[80:83], v[152:155], v[200:203], v[80:83]
	v_mfma_f32_16x16x32_bf16 v[72:75], v[160:163], v[200:203], v[72:75]
	v_mfma_f32_16x16x32_bf16 v[60:63], v[152:155], v[208:211], v[60:63]
	v_mfma_f32_16x16x32_bf16 v[48:51], v[160:163], v[208:211], v[48:51]
	v_mfma_f32_16x16x32_bf16 v[36:39], v[152:155], v[216:219], v[36:39]
	v_mfma_f32_16x16x32_bf16 v[32:35], v[160:163], v[216:219], v[32:35]
	s_setprio 0
	s_setprio 1
	v_mfma_f32_16x16x32_bf16 v[44:47], v[170:173], v[186:189], v[44:47]
	v_mfma_f32_16x16x32_bf16 v[26:29], v[178:181], v[186:189], v[26:29]
	v_mfma_f32_16x16x32_bf16 v[22:25], v[170:173], v[194:197], v[22:25]
	v_mfma_f32_16x16x32_bf16 v[18:21], v[178:181], v[194:197], v[18:21]
	v_mfma_f32_16x16x32_bf16 v[14:17], v[170:173], v[204:207], v[14:17]
	v_mfma_f32_16x16x32_bf16 v[10:13], v[178:181], v[204:207], v[10:13]
	v_mfma_f32_16x16x32_bf16 v[6:9], v[170:173], v[212:215], v[6:9]
	v_mfma_f32_16x16x32_bf16 v[2:5], v[178:181], v[212:215], v[2:5]
	v_mfma_f32_16x16x32_bf16 v[44:47], v[174:177], v[190:193], v[44:47]
	v_mfma_f32_16x16x32_bf16 v[26:29], v[182:185], v[190:193], v[26:29]
	v_mfma_f32_16x16x32_bf16 v[22:25], v[174:177], v[200:203], v[22:25]
	v_mfma_f32_16x16x32_bf16 v[18:21], v[182:185], v[200:203], v[18:21]
	v_mfma_f32_16x16x32_bf16 v[14:17], v[174:177], v[208:211], v[14:17]
	v_mfma_f32_16x16x32_bf16 v[10:13], v[182:185], v[208:211], v[10:13]
	v_mfma_f32_16x16x32_bf16 v[6:9], v[174:177], v[216:219], v[6:9]
	v_mfma_f32_16x16x32_bf16 v[2:5], v[182:185], v[216:219], v[2:5]
	s_setprio 0
	s_barrier
	s_add_i32 s64, s64, 2
	s_add_u32 s40, s40, 0x100
	s_addc_u32 s41, s41, 0
	s_cmpk_gt_u32 s64, 0x55
	s_cbranch_scc0 .LBB0_966
	s_add_u32 s40, s62, 0xffffff00
	s_addc_u32 s41, s63, -1
	s_and_b64 vcc, exec, s[38:39]
	s_cbranch_vccnz .LBB0_953
	v_mov_b32_e32 v2, 0
	s_mov_b32 s14, s55
	s_mov_b32 s48, s60
	s_mov_b64 s[20:21], s[22:23]
	s_mov_b32 s54, s61
	v_mov_b32_e32 v3, v2
	v_mov_b32_e32 v4, v2
	v_mov_b32_e32 v5, v2
	v_mov_b32_e32 v6, v2
	v_mov_b32_e32 v7, v2
	v_mov_b32_e32 v8, v2
	v_mov_b32_e32 v9, v2
	v_mov_b32_e32 v10, v2
	v_mov_b32_e32 v11, v2
	v_mov_b32_e32 v12, v2
	v_mov_b32_e32 v13, v2
	v_mov_b32_e32 v14, v2
	v_mov_b32_e32 v15, v2
	v_mov_b32_e32 v16, v2
	v_mov_b32_e32 v17, v2
	v_mov_b32_e32 v18, v2
	v_mov_b32_e32 v19, v2
	v_mov_b32_e32 v20, v2
	v_mov_b32_e32 v21, v2
	v_mov_b32_e32 v22, v2
	v_mov_b32_e32 v23, v2
	v_mov_b32_e32 v24, v2
	v_mov_b32_e32 v25, v2
	v_mov_b32_e32 v26, v2
	v_mov_b32_e32 v27, v2
	v_mov_b32_e32 v28, v2
	v_mov_b32_e32 v29, v2
	v_mov_b32_e32 v44, v2
	v_mov_b32_e32 v45, v2
	v_mov_b32_e32 v46, v2
	v_mov_b32_e32 v47, v2
	v_mov_b32_e32 v32, v2
	v_mov_b32_e32 v33, v2
	v_mov_b32_e32 v34, v2
	v_mov_b32_e32 v35, v2
	v_mov_b32_e32 v36, v2
	v_mov_b32_e32 v37, v2
	v_mov_b32_e32 v38, v2
	v_mov_b32_e32 v39, v2
	v_mov_b32_e32 v48, v2
	v_mov_b32_e32 v49, v2
	v_mov_b32_e32 v50, v2
	v_mov_b32_e32 v51, v2
	v_mov_b32_e32 v60, v2
	v_mov_b32_e32 v61, v2
	v_mov_b32_e32 v62, v2
	v_mov_b32_e32 v63, v2
	v_mov_b32_e32 v72, v2
	v_mov_b32_e32 v73, v2
	v_mov_b32_e32 v74, v2
	v_mov_b32_e32 v75, v2
	v_mov_b32_e32 v80, v2
	v_mov_b32_e32 v81, v2
	v_mov_b32_e32 v82, v2
	v_mov_b32_e32 v83, v2
	v_mov_b32_e32 v84, v2
	v_mov_b32_e32 v85, v2
	v_mov_b32_e32 v86, v2
	v_mov_b32_e32 v87, v2
	v_mov_b32_e32 v88, v2
	v_mov_b32_e32 v89, v2
	v_mov_b32_e32 v90, v2
	v_mov_b32_e32 v91, v2
	v_mov_b32_e32 v40, v2
	v_mov_b32_e32 v41, v2
	v_mov_b32_e32 v42, v2
	v_mov_b32_e32 v43, v2
	v_mov_b32_e32 v56, v2
	v_mov_b32_e32 v57, v2
	v_mov_b32_e32 v58, v2
	v_mov_b32_e32 v59, v2
	v_mov_b32_e32 v52, v2
	v_mov_b32_e32 v53, v2
	v_mov_b32_e32 v54, v2
	v_mov_b32_e32 v55, v2
	v_mov_b32_e32 v68, v2
	v_mov_b32_e32 v69, v2
	v_mov_b32_e32 v70, v2
	v_mov_b32_e32 v71, v2
	v_mov_b32_e32 v64, v2
	v_mov_b32_e32 v65, v2
	v_mov_b32_e32 v66, v2
	v_mov_b32_e32 v67, v2
	v_mov_b32_e32 v76, v2
	v_mov_b32_e32 v77, v2
	v_mov_b32_e32 v78, v2
	v_mov_b32_e32 v79, v2
	v_mov_b32_e32 v96, v2
	v_mov_b32_e32 v97, v2
	v_mov_b32_e32 v98, v2
	v_mov_b32_e32 v99, v2
	v_mov_b32_e32 v112, v2
	v_mov_b32_e32 v113, v2
	v_mov_b32_e32 v114, v2
	v_mov_b32_e32 v115, v2
	v_mov_b32_e32 v92, v2
	v_mov_b32_e32 v93, v2
	v_mov_b32_e32 v94, v2
	v_mov_b32_e32 v95, v2
	v_mov_b32_e32 v100, v2
	v_mov_b32_e32 v101, v2
	v_mov_b32_e32 v102, v2
	v_mov_b32_e32 v103, v2
	v_mov_b32_e32 v104, v2
	v_mov_b32_e32 v105, v2
	v_mov_b32_e32 v106, v2
	v_mov_b32_e32 v107, v2
	v_mov_b32_e32 v108, v2
	v_mov_b32_e32 v109, v2
	v_mov_b32_e32 v110, v2
	v_mov_b32_e32 v111, v2
	v_mov_b32_e32 v116, v2
	v_mov_b32_e32 v117, v2
	v_mov_b32_e32 v118, v2
	v_mov_b32_e32 v119, v2
	v_mov_b32_e32 v120, v2
	v_mov_b32_e32 v121, v2
	v_mov_b32_e32 v122, v2
	v_mov_b32_e32 v123, v2
	v_mov_b32_e32 v124, v2
	v_mov_b32_e32 v125, v2
	v_mov_b32_e32 v126, v2
	v_mov_b32_e32 v127, v2
	v_mov_b32_e32 v128, v2
	v_mov_b32_e32 v129, v2
	v_mov_b32_e32 v130, v2
	v_mov_b32_e32 v131, v2
	s_andn2_b64 vcc, exec, s[36:37]
	s_cbranch_vccnz .LBB0_954
